# SwiGLU epilogue ACT stores marked nt (streaming output, keeps GEMM operand tiles in L2)
# speedup vs baseline: 1.0034x; 1.0034x over previous
.LBB0_958:
	v_lshl_add_u32 v142, s22, 8, v144
	v_ashrrev_i32_e32 v143, 31, v142
	v_lshl_add_u64 v[200:201], v[142:143], 3, s[80:81]
	global_load_dwordx2 v[202:203], v[200:201], off
	global_load_dwordx2 v[204:205], v[200:201], off offset:128
	global_load_dwordx2 v[206:207], v[200:201], off offset:256
	global_load_dwordx2 v[208:209], v[200:201], off offset:384
	global_load_dwordx2 v[210:211], v[200:201], off offset:1024
	global_load_dwordx2 v[212:213], v[200:201], off offset:1152
	global_load_dwordx2 v[214:215], v[200:201], off offset:1280
	global_load_dwordx2 v[216:217], v[200:201], off offset:1408
	s_lshl_b32 s22, s14, 7
	s_ashr_i32 s23, s22, 31
	s_lshl_b64 s[22:23], s[22:23], 1
	s_andn2_b64 vcc, exec, s[2:3]
	s_waitcnt vmcnt(7)
	v_ffbh_u32_e32 v143, v203
	v_min_u32_e32 v143, 32, v143
	v_lshlrev_b64 v[148:149], v143, v[202:203]
	v_min_u32_e32 v147, 1, v148
	v_or_b32_e32 v147, v149, v147
	v_cvt_f32_u32_e32 v147, v147
	v_sub_u32_e32 v143, 32, v143
	v_ldexp_f32 v143, v147, v143
	v_mul_f32_e32 v143, 0x37800000, v143
	v_fmamk_f32 v143, v143, 0x3a800000, v195
	v_rsq_f32_e32 v148, v143
	s_nop 0
	v_pk_mul_f32 v[126:127], v[126:127], v[148:149] op_sel_hi:[1,0]
	s_nop 0
	v_mul_f32_e32 v143, 0xbfb8aa3b, v126
	v_exp_f32_e32 v143, v143
	v_pk_mul_f32 v[118:119], v[118:119], v[148:149] op_sel_hi:[1,0]
	v_pk_mul_f32 v[120:121], v[120:121], v[148:149] op_sel_hi:[1,0]
	v_pk_mul_f32 v[122:123], v[122:123], v[148:149] op_sel_hi:[1,0]
	v_add_f32_e32 v143, 1.0, v143
	v_rcp_f32_e32 v150, v143
	v_mul_f32_e32 v143, 0xbfb8aa3b, v127
	v_exp_f32_e32 v143, v143
	v_pk_mul_f32 v[114:115], v[114:115], v[148:149] op_sel_hi:[1,0]
	v_pk_mul_f32 v[116:117], v[116:117], v[148:149] op_sel_hi:[1,0]
	v_add_f32_e32 v143, 1.0, v143
	v_rcp_f32_e32 v151, v143
	s_nop 0
	v_pk_mul_f32 v[126:127], v[126:127], v[150:151]
	s_nop 0
	v_pk_mul_f32 v[118:119], v[118:119], v[126:127]
	v_pk_mul_f32 v[126:127], v[128:129], v[148:149] op_sel_hi:[1,0]
	s_nop 0
	v_mul_f32_e32 v128, 0xbfb8aa3b, v126
	v_mul_f32_e32 v129, 0xbfb8aa3b, v127
	v_exp_f32_e32 v128, v128
	v_exp_f32_e32 v129, v129
	v_add_f32_e32 v128, 1.0, v128
	v_add_f32_e32 v129, 1.0, v129
	v_rcp_f32_e32 v128, v128
	v_rcp_f32_e32 v129, v129
	s_nop 0
	v_pk_mul_f32 v[126:127], v[126:127], v[128:129]
	s_nop 0
	v_pk_mul_f32 v[120:121], v[120:121], v[126:127]
	v_mul_f32_e32 v126, 0xbfb8aa3b, v122
	v_mul_f32_e32 v127, 0xbfb8aa3b, v123
	v_exp_f32_e32 v126, v126
	v_exp_f32_e32 v127, v127
	v_add_f32_e32 v126, 1.0, v126
	v_add_f32_e32 v127, 1.0, v127
	v_rcp_f32_e32 v126, v126
	v_rcp_f32_e32 v127, v127
	s_nop 0
	v_pk_mul_f32 v[122:123], v[122:123], v[126:127]
	s_nop 0
	v_pk_mul_f32 v[122:123], v[114:115], v[122:123]
	v_pk_mul_f32 v[114:115], v[124:125], v[148:149] op_sel_hi:[1,0]
	s_nop 0
	v_mul_f32_e32 v124, 0xbfb8aa3b, v114
	v_mul_f32_e32 v125, 0xbfb8aa3b, v115
	v_exp_f32_e32 v124, v124
	v_exp_f32_e32 v125, v125
	v_add_f32_e32 v124, 1.0, v124
	v_add_f32_e32 v125, 1.0, v125
	v_rcp_f32_e32 v124, v124
	v_rcp_f32_e32 v125, v125
	s_nop 0
	v_pk_mul_f32 v[114:115], v[114:115], v[124:125]
	s_nop 0
	v_pk_mul_f32 v[124:125], v[116:117], v[114:115]
	v_cvt_pk_bf16_f32 v114, v118, v119
	v_mov_b64_e32 v[118:119], s[56:57]
	v_cvt_pk_bf16_f32 v115, v120, v121
	v_mad_i64_i32 v[120:121], s[12:13], v142, s83, v[118:119]
	v_lshl_add_u64 v[120:121], v[120:121], 0, s[22:23]
	v_lshl_add_u64 v[120:121], v[120:121], 0, s[90:91]
	v_cvt_pk_bf16_f32 v116, v122, v123
	v_cvt_pk_bf16_f32 v117, v124, v125
	v_lshl_add_u64 v[120:121], v[120:121], 0, v[0:1]
	global_store_dwordx4 v[120:121], v[114:117], off nt
	s_nop 1
	v_or_b32_e32 v114, 16, v142
	v_ashrrev_i32_e32 v115, 31, v114
	s_waitcnt vmcnt(7)
	v_ffbh_u32_e32 v115, v205
	v_min_u32_e32 v115, 32, v115
	v_lshlrev_b64 v[116:117], v115, v[204:205]
	v_min_u32_e32 v116, 1, v116
	v_or_b32_e32 v116, v117, v116
	v_cvt_f32_u32_e32 v116, v116
	v_sub_u32_e32 v115, 32, v115
	v_ldexp_f32 v115, v116, v115
	v_mul_f32_e32 v115, 0x37800000, v115
	v_fmamk_f32 v115, v115, 0x3a800000, v195
	v_rsq_f32_e32 v116, v115
	s_nop 0
	v_pk_mul_f32 v[110:111], v[110:111], v[116:117] op_sel_hi:[1,0]
	s_nop 0
	v_mul_f32_e32 v115, 0xbfb8aa3b, v110
	v_exp_f32_e32 v115, v115
	v_pk_mul_f32 v[102:103], v[102:103], v[116:117] op_sel_hi:[1,0]
	v_pk_mul_f32 v[104:105], v[104:105], v[116:117] op_sel_hi:[1,0]
	v_pk_mul_f32 v[106:107], v[106:107], v[116:117] op_sel_hi:[1,0]
	v_add_f32_e32 v115, 1.0, v115
	v_rcp_f32_e32 v120, v115
	v_mul_f32_e32 v115, 0xbfb8aa3b, v111
	v_exp_f32_e32 v115, v115
	v_pk_mul_f32 v[98:99], v[98:99], v[116:117] op_sel_hi:[1,0]
	v_pk_mul_f32 v[100:101], v[100:101], v[116:117] op_sel_hi:[1,0]
	v_add_f32_e32 v115, 1.0, v115
	v_rcp_f32_e32 v121, v115
	s_nop 0
	v_pk_mul_f32 v[110:111], v[110:111], v[120:121]
	s_nop 0
	v_pk_mul_f32 v[102:103], v[102:103], v[110:111]
	v_pk_mul_f32 v[110:111], v[112:113], v[116:117] op_sel_hi:[1,0]
	s_nop 0
	v_mul_f32_e32 v112, 0xbfb8aa3b, v110
	v_mul_f32_e32 v113, 0xbfb8aa3b, v111
	v_exp_f32_e32 v112, v112
	v_exp_f32_e32 v113, v113
	v_add_f32_e32 v112, 1.0, v112
	v_add_f32_e32 v113, 1.0, v113
	v_rcp_f32_e32 v112, v112
	v_rcp_f32_e32 v113, v113
	s_nop 0
	v_pk_mul_f32 v[110:111], v[110:111], v[112:113]
	s_nop 0
	v_pk_mul_f32 v[104:105], v[104:105], v[110:111]
	v_mul_f32_e32 v110, 0xbfb8aa3b, v106
	v_mul_f32_e32 v111, 0xbfb8aa3b, v107
	v_exp_f32_e32 v110, v110
	v_exp_f32_e32 v111, v111
	v_add_f32_e32 v110, 1.0, v110
	v_add_f32_e32 v111, 1.0, v111
	v_rcp_f32_e32 v110, v110
	v_rcp_f32_e32 v111, v111
	s_nop 0
	v_pk_mul_f32 v[106:107], v[106:107], v[110:111]
	s_nop 0
	v_pk_mul_f32 v[106:107], v[98:99], v[106:107]
	v_pk_mul_f32 v[98:99], v[108:109], v[116:117] op_sel_hi:[1,0]
	s_nop 0
	v_mul_f32_e32 v108, 0xbfb8aa3b, v98
	v_mul_f32_e32 v109, 0xbfb8aa3b, v99
	v_exp_f32_e32 v108, v108
	v_exp_f32_e32 v109, v109
	v_add_f32_e32 v108, 1.0, v108
	v_add_f32_e32 v109, 1.0, v109
	v_rcp_f32_e32 v108, v108
	v_rcp_f32_e32 v109, v109
	s_nop 0
	v_pk_mul_f32 v[98:99], v[98:99], v[108:109]
	s_nop 0
	v_pk_mul_f32 v[108:109], v[100:101], v[98:99]
	v_cvt_pk_bf16_f32 v98, v102, v103
	v_mad_i64_i32 v[102:103], s[12:13], v114, s83, v[118:119]
	v_lshl_add_u64 v[102:103], v[102:103], 0, s[22:23]
	v_lshl_add_u64 v[102:103], v[102:103], 0, s[90:91]
	v_cvt_pk_bf16_f32 v99, v104, v105
	v_cvt_pk_bf16_f32 v100, v106, v107
	v_cvt_pk_bf16_f32 v101, v108, v109
	v_lshl_add_u64 v[102:103], v[102:103], 0, v[0:1]
	global_store_dwordx4 v[102:103], v[98:101], off nt
	s_nop 1
	v_or_b32_e32 v98, 32, v142
	v_ashrrev_i32_e32 v99, 31, v98
	s_waitcnt vmcnt(7)
	v_ffbh_u32_e32 v99, v207
	v_min_u32_e32 v99, 32, v99
	v_lshlrev_b64 v[100:101], v99, v[206:207]
	v_min_u32_e32 v100, 1, v100
	v_or_b32_e32 v100, v101, v100
	v_cvt_f32_u32_e32 v100, v100
	v_sub_u32_e32 v99, 32, v99
	v_ldexp_f32 v99, v100, v99
	v_mul_f32_e32 v99, 0x37800000, v99
	v_fmamk_f32 v99, v99, 0x3a800000, v195
	v_rsq_f32_e32 v100, v99
	s_nop 0
	v_pk_mul_f32 v[94:95], v[94:95], v[100:101] op_sel_hi:[1,0]
	s_nop 0
	v_mul_f32_e32 v99, 0xbfb8aa3b, v94
	v_exp_f32_e32 v99, v99
	v_pk_mul_f32 v[86:87], v[86:87], v[100:101] op_sel_hi:[1,0]
	v_pk_mul_f32 v[88:89], v[88:89], v[100:101] op_sel_hi:[1,0]
	v_pk_mul_f32 v[90:91], v[90:91], v[100:101] op_sel_hi:[1,0]
	v_add_f32_e32 v99, 1.0, v99
	v_rcp_f32_e32 v102, v99
	v_mul_f32_e32 v99, 0xbfb8aa3b, v95
	v_exp_f32_e32 v99, v99
	v_pk_mul_f32 v[82:83], v[82:83], v[100:101] op_sel_hi:[1,0]
	v_pk_mul_f32 v[84:85], v[84:85], v[100:101] op_sel_hi:[1,0]
	v_add_f32_e32 v99, 1.0, v99
	v_rcp_f32_e32 v103, v99
	s_nop 0
	v_pk_mul_f32 v[94:95], v[94:95], v[102:103]
	s_nop 0
	v_pk_mul_f32 v[86:87], v[86:87], v[94:95]
	v_pk_mul_f32 v[94:95], v[96:97], v[100:101] op_sel_hi:[1,0]
	s_nop 0
	v_mul_f32_e32 v96, 0xbfb8aa3b, v94
	v_mul_f32_e32 v97, 0xbfb8aa3b, v95
	v_exp_f32_e32 v96, v96
	v_exp_f32_e32 v97, v97
	v_add_f32_e32 v96, 1.0, v96
	v_add_f32_e32 v97, 1.0, v97
	v_rcp_f32_e32 v96, v96
	v_rcp_f32_e32 v97, v97
	s_nop 0
	v_pk_mul_f32 v[94:95], v[94:95], v[96:97]
	s_nop 0
	v_pk_mul_f32 v[88:89], v[88:89], v[94:95]
	v_mul_f32_e32 v94, 0xbfb8aa3b, v90
	v_mul_f32_e32 v95, 0xbfb8aa3b, v91
	v_exp_f32_e32 v94, v94
	v_exp_f32_e32 v95, v95
	v_add_f32_e32 v94, 1.0, v94
	v_add_f32_e32 v95, 1.0, v95
	v_rcp_f32_e32 v94, v94
	v_rcp_f32_e32 v95, v95
	s_nop 0
	v_pk_mul_f32 v[90:91], v[90:91], v[94:95]
	s_nop 0
	v_pk_mul_f32 v[90:91], v[82:83], v[90:91]
	v_pk_mul_f32 v[82:83], v[92:93], v[100:101] op_sel_hi:[1,0]
	s_nop 0
	v_mul_f32_e32 v92, 0xbfb8aa3b, v82
	v_mul_f32_e32 v93, 0xbfb8aa3b, v83
	v_exp_f32_e32 v92, v92
	v_exp_f32_e32 v93, v93
	v_add_f32_e32 v92, 1.0, v92
	v_add_f32_e32 v93, 1.0, v93
	v_rcp_f32_e32 v92, v92
	v_rcp_f32_e32 v93, v93
	s_nop 0
	v_pk_mul_f32 v[82:83], v[82:83], v[92:93]
	s_nop 0
	v_pk_mul_f32 v[92:93], v[84:85], v[82:83]
	v_cvt_pk_bf16_f32 v82, v86, v87
	v_mad_i64_i32 v[86:87], s[12:13], v98, s83, v[118:119]
	v_lshl_add_u64 v[86:87], v[86:87], 0, s[22:23]
	v_lshl_add_u64 v[86:87], v[86:87], 0, s[90:91]
	v_cvt_pk_bf16_f32 v83, v88, v89
	v_cvt_pk_bf16_f32 v84, v90, v91
	v_cvt_pk_bf16_f32 v85, v92, v93
	v_lshl_add_u64 v[86:87], v[86:87], 0, v[0:1]
	global_store_dwordx4 v[86:87], v[82:85], off nt
	s_nop 1
	v_or_b32_e32 v82, 48, v142
	v_ashrrev_i32_e32 v83, 31, v82
	s_waitcnt vmcnt(7)
	v_ffbh_u32_e32 v83, v209
	v_min_u32_e32 v83, 32, v83
	v_lshlrev_b64 v[84:85], v83, v[208:209]
	v_min_u32_e32 v84, 1, v84
	v_or_b32_e32 v84, v85, v84
	v_cvt_f32_u32_e32 v84, v84
	v_sub_u32_e32 v83, 32, v83
	v_ldexp_f32 v83, v84, v83
	v_mul_f32_e32 v83, 0x37800000, v83
	v_fmamk_f32 v83, v83, 0x3a800000, v195
	v_rsq_f32_e32 v84, v83
	s_nop 0
	v_pk_mul_f32 v[78:79], v[78:79], v[84:85] op_sel_hi:[1,0]
	s_nop 0
	v_mul_f32_e32 v83, 0xbfb8aa3b, v78
	v_exp_f32_e32 v83, v83
	v_pk_mul_f32 v[70:71], v[70:71], v[84:85] op_sel_hi:[1,0]
	v_pk_mul_f32 v[72:73], v[72:73], v[84:85] op_sel_hi:[1,0]
	v_pk_mul_f32 v[74:75], v[74:75], v[84:85] op_sel_hi:[1,0]
	v_add_f32_e32 v83, 1.0, v83
	v_rcp_f32_e32 v86, v83
	v_mul_f32_e32 v83, 0xbfb8aa3b, v79
	v_exp_f32_e32 v83, v83
	v_pk_mul_f32 v[66:67], v[66:67], v[84:85] op_sel_hi:[1,0]
	v_pk_mul_f32 v[68:69], v[68:69], v[84:85] op_sel_hi:[1,0]
	v_add_f32_e32 v83, 1.0, v83
	v_rcp_f32_e32 v87, v83
	s_nop 0
	v_pk_mul_f32 v[78:79], v[78:79], v[86:87]
	s_nop 0
	v_pk_mul_f32 v[70:71], v[70:71], v[78:79]
	v_pk_mul_f32 v[78:79], v[80:81], v[84:85] op_sel_hi:[1,0]
	s_nop 0
	v_mul_f32_e32 v80, 0xbfb8aa3b, v78
	v_mul_f32_e32 v81, 0xbfb8aa3b, v79
	v_exp_f32_e32 v80, v80
	v_exp_f32_e32 v81, v81
	v_add_f32_e32 v80, 1.0, v80
	v_add_f32_e32 v81, 1.0, v81
	v_rcp_f32_e32 v80, v80
	v_rcp_f32_e32 v81, v81
	s_nop 0
	v_pk_mul_f32 v[78:79], v[78:79], v[80:81]
	s_nop 0
	v_pk_mul_f32 v[72:73], v[72:73], v[78:79]
	v_mul_f32_e32 v78, 0xbfb8aa3b, v74
	v_mul_f32_e32 v79, 0xbfb8aa3b, v75
	v_exp_f32_e32 v78, v78
	v_exp_f32_e32 v79, v79
	v_add_f32_e32 v78, 1.0, v78
	v_add_f32_e32 v79, 1.0, v79
	v_rcp_f32_e32 v78, v78
	v_rcp_f32_e32 v79, v79
	s_nop 0
	v_pk_mul_f32 v[74:75], v[74:75], v[78:79]
	s_nop 0
	v_pk_mul_f32 v[74:75], v[66:67], v[74:75]
	v_pk_mul_f32 v[66:67], v[76:77], v[84:85] op_sel_hi:[1,0]
	s_nop 0
	v_mul_f32_e32 v76, 0xbfb8aa3b, v66
	v_mul_f32_e32 v77, 0xbfb8aa3b, v67
	v_exp_f32_e32 v76, v76
	v_exp_f32_e32 v77, v77
	v_add_f32_e32 v76, 1.0, v76
	v_add_f32_e32 v77, 1.0, v77
	v_rcp_f32_e32 v76, v76
	v_rcp_f32_e32 v77, v77
	s_nop 0
	v_pk_mul_f32 v[66:67], v[66:67], v[76:77]
	s_nop 0
	v_pk_mul_f32 v[76:77], v[68:69], v[66:67]
	v_cvt_pk_bf16_f32 v66, v70, v71
	v_mad_i64_i32 v[70:71], s[12:13], v82, s83, v[118:119]
	v_lshl_add_u64 v[70:71], v[70:71], 0, s[22:23]
	v_lshl_add_u64 v[70:71], v[70:71], 0, s[90:91]
	v_cvt_pk_bf16_f32 v67, v72, v73
	v_cvt_pk_bf16_f32 v68, v74, v75
	v_cvt_pk_bf16_f32 v69, v76, v77
	v_lshl_add_u64 v[70:71], v[70:71], 0, v[0:1]
	global_store_dwordx4 v[70:71], v[66:69], off nt
	s_nop 1
	v_add_u32_e32 v66, 0x80, v142
	v_ashrrev_i32_e32 v67, 31, v66
	s_waitcnt vmcnt(7)
	v_ffbh_u32_e32 v67, v211
	v_min_u32_e32 v67, 32, v67
	v_lshlrev_b64 v[68:69], v67, v[210:211]
	v_min_u32_e32 v68, 1, v68
	v_or_b32_e32 v68, v69, v68
	v_cvt_f32_u32_e32 v68, v68
	v_sub_u32_e32 v67, 32, v67
	v_ldexp_f32 v67, v68, v67
	v_mul_f32_e32 v67, 0x37800000, v67
	v_fmamk_f32 v67, v67, 0x3a800000, v195
	v_rsq_f32_e32 v68, v67
	s_nop 0
	v_pk_mul_f32 v[62:63], v[62:63], v[68:69] op_sel_hi:[1,0]
	s_nop 0
	v_mul_f32_e32 v67, 0xbfb8aa3b, v62
	v_exp_f32_e32 v67, v67
	v_pk_mul_f32 v[54:55], v[54:55], v[68:69] op_sel_hi:[1,0]
	v_pk_mul_f32 v[56:57], v[56:57], v[68:69] op_sel_hi:[1,0]
	v_pk_mul_f32 v[58:59], v[58:59], v[68:69] op_sel_hi:[1,0]
	v_add_f32_e32 v67, 1.0, v67
	v_rcp_f32_e32 v70, v67
	v_mul_f32_e32 v67, 0xbfb8aa3b, v63
	v_exp_f32_e32 v67, v67
	v_pk_mul_f32 v[50:51], v[50:51], v[68:69] op_sel_hi:[1,0]
	v_pk_mul_f32 v[52:53], v[52:53], v[68:69] op_sel_hi:[1,0]
	v_add_f32_e32 v67, 1.0, v67
	v_rcp_f32_e32 v71, v67
	s_nop 0
	v_pk_mul_f32 v[62:63], v[62:63], v[70:71]
	s_nop 0
	v_pk_mul_f32 v[54:55], v[54:55], v[62:63]
	v_pk_mul_f32 v[62:63], v[64:65], v[68:69] op_sel_hi:[1,0]
	s_nop 0
	v_mul_f32_e32 v64, 0xbfb8aa3b, v62
	v_mul_f32_e32 v65, 0xbfb8aa3b, v63
	v_exp_f32_e32 v64, v64
	v_exp_f32_e32 v65, v65
	v_add_f32_e32 v64, 1.0, v64
	v_add_f32_e32 v65, 1.0, v65
	v_rcp_f32_e32 v64, v64
	v_rcp_f32_e32 v65, v65
	s_nop 0
	v_pk_mul_f32 v[62:63], v[62:63], v[64:65]
	s_nop 0
	v_pk_mul_f32 v[56:57], v[56:57], v[62:63]
	v_mul_f32_e32 v62, 0xbfb8aa3b, v58
	v_mul_f32_e32 v63, 0xbfb8aa3b, v59
	v_exp_f32_e32 v62, v62
	v_exp_f32_e32 v63, v63
	v_add_f32_e32 v62, 1.0, v62
	v_add_f32_e32 v63, 1.0, v63
	v_rcp_f32_e32 v62, v62
	v_rcp_f32_e32 v63, v63
	s_nop 0
	v_pk_mul_f32 v[58:59], v[58:59], v[62:63]
	s_nop 0
	v_pk_mul_f32 v[58:59], v[50:51], v[58:59]
	v_pk_mul_f32 v[50:51], v[60:61], v[68:69] op_sel_hi:[1,0]
	s_nop 0
	v_mul_f32_e32 v60, 0xbfb8aa3b, v50
	v_mul_f32_e32 v61, 0xbfb8aa3b, v51
	v_exp_f32_e32 v60, v60
	v_exp_f32_e32 v61, v61
	v_add_f32_e32 v60, 1.0, v60
	v_add_f32_e32 v61, 1.0, v61
	v_rcp_f32_e32 v60, v60
	v_rcp_f32_e32 v61, v61
	s_nop 0
	v_pk_mul_f32 v[50:51], v[50:51], v[60:61]
	s_nop 0
	v_pk_mul_f32 v[60:61], v[52:53], v[50:51]
	v_cvt_pk_bf16_f32 v50, v54, v55
	v_mad_i64_i32 v[54:55], s[12:13], v66, s83, v[118:119]
	v_lshl_add_u64 v[54:55], v[54:55], 0, s[22:23]
	v_lshl_add_u64 v[54:55], v[54:55], 0, s[90:91]
	v_cvt_pk_bf16_f32 v51, v56, v57
	v_cvt_pk_bf16_f32 v52, v58, v59
	v_cvt_pk_bf16_f32 v53, v60, v61
	v_lshl_add_u64 v[54:55], v[54:55], 0, v[0:1]
	global_store_dwordx4 v[54:55], v[50:53], off nt
	s_nop 1
	v_add_u32_e32 v50, 0x90, v142
	v_ashrrev_i32_e32 v51, 31, v50
	s_waitcnt vmcnt(7)
	v_ffbh_u32_e32 v51, v213
	v_min_u32_e32 v51, 32, v51
	v_lshlrev_b64 v[52:53], v51, v[212:213]
	v_min_u32_e32 v52, 1, v52
	v_or_b32_e32 v52, v53, v52
	v_cvt_f32_u32_e32 v52, v52
	v_sub_u32_e32 v51, 32, v51
	v_ldexp_f32 v51, v52, v51
	v_mul_f32_e32 v51, 0x37800000, v51
	v_fmamk_f32 v51, v51, 0x3a800000, v195
	v_rsq_f32_e32 v52, v51
	s_nop 0
	v_pk_mul_f32 v[46:47], v[46:47], v[52:53] op_sel_hi:[1,0]
	s_nop 0
	v_mul_f32_e32 v51, 0xbfb8aa3b, v46
	v_exp_f32_e32 v51, v51
	v_pk_mul_f32 v[38:39], v[38:39], v[52:53] op_sel_hi:[1,0]
	v_pk_mul_f32 v[40:41], v[40:41], v[52:53] op_sel_hi:[1,0]
	v_pk_mul_f32 v[42:43], v[42:43], v[52:53] op_sel_hi:[1,0]
	v_add_f32_e32 v51, 1.0, v51
	v_rcp_f32_e32 v54, v51
	v_mul_f32_e32 v51, 0xbfb8aa3b, v47
	v_exp_f32_e32 v51, v51
	v_pk_mul_f32 v[34:35], v[34:35], v[52:53] op_sel_hi:[1,0]
	v_pk_mul_f32 v[36:37], v[36:37], v[52:53] op_sel_hi:[1,0]
	v_add_f32_e32 v51, 1.0, v51
	v_rcp_f32_e32 v55, v51
	s_nop 0
	v_pk_mul_f32 v[46:47], v[46:47], v[54:55]
	s_nop 0
	v_pk_mul_f32 v[38:39], v[38:39], v[46:47]
	v_pk_mul_f32 v[46:47], v[48:49], v[52:53] op_sel_hi:[1,0]
	s_nop 0
	v_mul_f32_e32 v48, 0xbfb8aa3b, v46
	v_mul_f32_e32 v49, 0xbfb8aa3b, v47
	v_exp_f32_e32 v48, v48
	v_exp_f32_e32 v49, v49
	v_add_f32_e32 v48, 1.0, v48
	v_add_f32_e32 v49, 1.0, v49
	v_rcp_f32_e32 v48, v48
	v_rcp_f32_e32 v49, v49
	s_nop 0
	v_pk_mul_f32 v[46:47], v[46:47], v[48:49]
	s_nop 0
	v_pk_mul_f32 v[40:41], v[40:41], v[46:47]
	v_mul_f32_e32 v46, 0xbfb8aa3b, v42
	v_mul_f32_e32 v47, 0xbfb8aa3b, v43
	v_exp_f32_e32 v46, v46
	v_exp_f32_e32 v47, v47
	v_add_f32_e32 v46, 1.0, v46
	v_add_f32_e32 v47, 1.0, v47
	v_rcp_f32_e32 v46, v46
	v_rcp_f32_e32 v47, v47
	s_nop 0
	v_pk_mul_f32 v[42:43], v[42:43], v[46:47]
	s_nop 0
	v_pk_mul_f32 v[42:43], v[34:35], v[42:43]
	v_pk_mul_f32 v[34:35], v[44:45], v[52:53] op_sel_hi:[1,0]
	s_nop 0
	v_mul_f32_e32 v44, 0xbfb8aa3b, v34
	v_mul_f32_e32 v45, 0xbfb8aa3b, v35
	v_exp_f32_e32 v44, v44
	v_exp_f32_e32 v45, v45
	v_add_f32_e32 v44, 1.0, v44
	v_add_f32_e32 v45, 1.0, v45
	v_rcp_f32_e32 v44, v44
	v_rcp_f32_e32 v45, v45
	s_nop 0
	v_pk_mul_f32 v[34:35], v[34:35], v[44:45]
	s_nop 0
	v_pk_mul_f32 v[44:45], v[36:37], v[34:35]
	v_cvt_pk_bf16_f32 v34, v38, v39
	v_mad_i64_i32 v[38:39], s[12:13], v50, s83, v[118:119]
	v_lshl_add_u64 v[38:39], v[38:39], 0, s[22:23]
	v_lshl_add_u64 v[38:39], v[38:39], 0, s[90:91]
	v_cvt_pk_bf16_f32 v35, v40, v41
	v_cvt_pk_bf16_f32 v36, v42, v43
	v_cvt_pk_bf16_f32 v37, v44, v45
	v_lshl_add_u64 v[38:39], v[38:39], 0, v[0:1]
	global_store_dwordx4 v[38:39], v[34:37], off nt
	s_nop 1
	v_add_u32_e32 v34, 0xa0, v142
	v_ashrrev_i32_e32 v35, 31, v34
	s_waitcnt vmcnt(7)
	v_ffbh_u32_e32 v35, v215
	v_min_u32_e32 v35, 32, v35
	v_lshlrev_b64 v[36:37], v35, v[214:215]
	v_min_u32_e32 v36, 1, v36
	v_or_b32_e32 v36, v37, v36
	v_cvt_f32_u32_e32 v36, v36
	v_sub_u32_e32 v35, 32, v35
	v_ldexp_f32 v35, v36, v35
	v_mul_f32_e32 v35, 0x37800000, v35
	v_fmamk_f32 v35, v35, 0x3a800000, v195
	v_rsq_f32_e32 v36, v35
	s_nop 0
	v_pk_mul_f32 v[30:31], v[30:31], v[36:37] op_sel_hi:[1,0]
	s_nop 0
	v_mul_f32_e32 v35, 0xbfb8aa3b, v30
	v_exp_f32_e32 v35, v35
	v_pk_mul_f32 v[22:23], v[22:23], v[36:37] op_sel_hi:[1,0]
	v_pk_mul_f32 v[24:25], v[24:25], v[36:37] op_sel_hi:[1,0]
	v_pk_mul_f32 v[26:27], v[26:27], v[36:37] op_sel_hi:[1,0]
	v_add_f32_e32 v35, 1.0, v35
	v_rcp_f32_e32 v38, v35
	v_mul_f32_e32 v35, 0xbfb8aa3b, v31
	v_exp_f32_e32 v35, v35
	v_pk_mul_f32 v[18:19], v[18:19], v[36:37] op_sel_hi:[1,0]
	v_pk_mul_f32 v[20:21], v[20:21], v[36:37] op_sel_hi:[1,0]
	v_add_f32_e32 v35, 1.0, v35
	v_rcp_f32_e32 v39, v35
	s_nop 0
	v_pk_mul_f32 v[30:31], v[30:31], v[38:39]
	s_nop 0
	v_pk_mul_f32 v[22:23], v[22:23], v[30:31]
	v_pk_mul_f32 v[30:31], v[32:33], v[36:37] op_sel_hi:[1,0]
	s_nop 0
	v_mul_f32_e32 v32, 0xbfb8aa3b, v30
	v_mul_f32_e32 v33, 0xbfb8aa3b, v31
	v_exp_f32_e32 v32, v32
	v_exp_f32_e32 v33, v33
	v_add_f32_e32 v32, 1.0, v32
	v_add_f32_e32 v33, 1.0, v33
	v_rcp_f32_e32 v32, v32
	v_rcp_f32_e32 v33, v33
	s_nop 0
	v_pk_mul_f32 v[30:31], v[30:31], v[32:33]
	s_nop 0
	v_pk_mul_f32 v[24:25], v[24:25], v[30:31]
	v_mul_f32_e32 v30, 0xbfb8aa3b, v26
	v_mul_f32_e32 v31, 0xbfb8aa3b, v27
	v_exp_f32_e32 v30, v30
	v_exp_f32_e32 v31, v31
	v_add_f32_e32 v30, 1.0, v30
	v_add_f32_e32 v31, 1.0, v31
	v_rcp_f32_e32 v30, v30
	v_rcp_f32_e32 v31, v31
	s_nop 0
	v_pk_mul_f32 v[26:27], v[26:27], v[30:31]
	s_nop 0
	v_pk_mul_f32 v[26:27], v[18:19], v[26:27]
	v_pk_mul_f32 v[18:19], v[28:29], v[36:37] op_sel_hi:[1,0]
	s_nop 0
	v_mul_f32_e32 v28, 0xbfb8aa3b, v18
	v_mul_f32_e32 v29, 0xbfb8aa3b, v19
	v_exp_f32_e32 v28, v28
	v_exp_f32_e32 v29, v29
	v_add_f32_e32 v28, 1.0, v28
	v_add_f32_e32 v29, 1.0, v29
	v_rcp_f32_e32 v28, v28
	v_rcp_f32_e32 v29, v29
	s_nop 0
	v_pk_mul_f32 v[18:19], v[18:19], v[28:29]
	s_nop 0
	v_pk_mul_f32 v[28:29], v[20:21], v[18:19]
	v_cvt_pk_bf16_f32 v18, v22, v23
	v_mad_i64_i32 v[22:23], s[12:13], v34, s83, v[118:119]
	v_lshl_add_u64 v[22:23], v[22:23], 0, s[22:23]
	v_lshl_add_u64 v[22:23], v[22:23], 0, s[90:91]
	v_cvt_pk_bf16_f32 v19, v24, v25
	v_cvt_pk_bf16_f32 v20, v26, v27
	v_cvt_pk_bf16_f32 v21, v28, v29
	v_lshl_add_u64 v[22:23], v[22:23], 0, v[0:1]
	global_store_dwordx4 v[22:23], v[18:21], off nt
	s_nop 1
	v_add_u32_e32 v18, 0xb0, v142
	v_ashrrev_i32_e32 v19, 31, v18
	s_waitcnt vmcnt(7)
	v_ffbh_u32_e32 v19, v217
	v_min_u32_e32 v19, 32, v19
	v_lshlrev_b64 v[20:21], v19, v[216:217]
	v_min_u32_e32 v20, 1, v20
	v_or_b32_e32 v20, v21, v20
	v_cvt_f32_u32_e32 v20, v20
	v_sub_u32_e32 v19, 32, v19
	v_ldexp_f32 v19, v20, v19
	v_mul_f32_e32 v19, 0x37800000, v19
	v_fmamk_f32 v19, v19, 0x3a800000, v195
	v_rsq_f32_e32 v20, v19
	s_nop 0
	v_pk_mul_f32 v[14:15], v[14:15], v[20:21] op_sel_hi:[1,0]
	s_nop 0
	v_mul_f32_e32 v19, 0xbfb8aa3b, v14
	v_exp_f32_e32 v19, v19
	v_pk_mul_f32 v[6:7], v[6:7], v[20:21] op_sel_hi:[1,0]
	v_pk_mul_f32 v[8:9], v[8:9], v[20:21] op_sel_hi:[1,0]
	v_pk_mul_f32 v[10:11], v[10:11], v[20:21] op_sel_hi:[1,0]
	v_add_f32_e32 v19, 1.0, v19
	v_rcp_f32_e32 v22, v19
	v_mul_f32_e32 v19, 0xbfb8aa3b, v15
	v_exp_f32_e32 v19, v19
	v_pk_mul_f32 v[2:3], v[2:3], v[20:21] op_sel_hi:[1,0]
	v_pk_mul_f32 v[4:5], v[4:5], v[20:21] op_sel_hi:[1,0]
	v_add_f32_e32 v19, 1.0, v19
	v_rcp_f32_e32 v23, v19
	s_nop 0
	v_pk_mul_f32 v[14:15], v[14:15], v[22:23]
	s_nop 0
	v_pk_mul_f32 v[6:7], v[6:7], v[14:15]
	v_pk_mul_f32 v[14:15], v[16:17], v[20:21] op_sel_hi:[1,0]
	s_nop 0
	v_mul_f32_e32 v16, 0xbfb8aa3b, v14
	v_mul_f32_e32 v17, 0xbfb8aa3b, v15
	v_exp_f32_e32 v16, v16
	v_exp_f32_e32 v17, v17
	v_add_f32_e32 v16, 1.0, v16
	v_add_f32_e32 v17, 1.0, v17
	v_rcp_f32_e32 v16, v16
	v_rcp_f32_e32 v17, v17
	s_nop 0
	v_pk_mul_f32 v[14:15], v[14:15], v[16:17]
	s_nop 0
	v_pk_mul_f32 v[8:9], v[8:9], v[14:15]
	v_mul_f32_e32 v14, 0xbfb8aa3b, v10
	v_mul_f32_e32 v15, 0xbfb8aa3b, v11
	v_exp_f32_e32 v14, v14
	v_exp_f32_e32 v15, v15
	v_add_f32_e32 v14, 1.0, v14
	v_add_f32_e32 v15, 1.0, v15
	v_rcp_f32_e32 v14, v14
	v_rcp_f32_e32 v15, v15
	s_nop 0
	v_pk_mul_f32 v[10:11], v[10:11], v[14:15]
	s_nop 0
	v_pk_mul_f32 v[10:11], v[2:3], v[10:11]
	v_pk_mul_f32 v[2:3], v[12:13], v[20:21] op_sel_hi:[1,0]
	s_nop 0
	v_mul_f32_e32 v12, 0xbfb8aa3b, v2
	v_mul_f32_e32 v13, 0xbfb8aa3b, v3
	v_exp_f32_e32 v12, v12
	v_exp_f32_e32 v13, v13
	v_add_f32_e32 v12, 1.0, v12
	v_add_f32_e32 v13, 1.0, v13
	v_rcp_f32_e32 v12, v12
	v_rcp_f32_e32 v13, v13
	s_nop 0
	v_pk_mul_f32 v[2:3], v[2:3], v[12:13]
	s_nop 0
	v_pk_mul_f32 v[12:13], v[4:5], v[2:3]
	v_cvt_pk_bf16_f32 v2, v6, v7
	v_mad_i64_i32 v[6:7], s[12:13], v18, s83, v[118:119]
	v_lshl_add_u64 v[6:7], v[6:7], 0, s[22:23]
	v_lshl_add_u64 v[6:7], v[6:7], 0, s[90:91]
	v_cvt_pk_bf16_f32 v3, v8, v9
	v_cvt_pk_bf16_f32 v4, v10, v11
	v_cvt_pk_bf16_f32 v5, v12, v13
	v_lshl_add_u64 v[6:7], v[6:7], 0, v[0:1]
	global_store_dwordx4 v[6:7], v[2:5], off nt
	s_mov_b64 s[22:23], -1
	s_cbranch_vccnz .LBB0_951
	s_andn2_b64 vcc, exec, s[6:7]
	s_cbranch_vccnz .LBB0_950
	s_barrier
	s_branch .LBB0_950
